# w13: next K-step's 8 DMA loads issued right after the barrier, ahead of the fragment reads and first MFMA group
# baseline (speedup 1.0000x reference)
.Lw13_loop:
	s_waitcnt vmcnt(0)
	s_barrier
	s_mov_b32 m0, s43
	s_nop 0
	global_load_lds_dwordx4 v168, s[22:23]
	s_add_u32 m0, m0, 0x2000
	s_nop 0
	global_load_lds_dwordx4 v169, s[22:23]
	s_add_u32 m0, m0, 0x2000
	s_nop 0
	global_load_lds_dwordx4 v170, s[22:23]
	s_add_u32 m0, m0, 0x2000
	s_nop 0
	global_load_lds_dwordx4 v171, s[22:23]
	s_add_u32 m0, m0, 0x2000
	s_nop 0
	global_load_lds_dwordx4 v168, s[24:25]
	s_add_u32 m0, m0, 0x2000
	s_nop 0
	global_load_lds_dwordx4 v169, s[24:25]
	s_add_u32 m0, m0, 0x2000
	s_nop 0
	global_load_lds_dwordx4 v170, s[24:25]
	s_add_u32 m0, m0, 0x2000
	s_nop 0
	global_load_lds_dwordx4 v171, s[24:25]
	s_add_u32 s22, s22, 0x80
	s_addc_u32 s23, s23, 0
	s_add_u32 s24, s24, 0x80
	s_addc_u32 s25, s25, 0
	ds_read_b128 v[4:7], v172
	ds_read_b128 v[8:11], v172 offset:4096
	ds_read_b128 v[12:15], v192 offset:32768
	ds_read_b128 v[246:249], v192 offset:36864
	ds_read_b128 v[214:217], v192 offset:40960
	ds_read_b128 v[218:221], v192 offset:45056
	ds_read_b128 v[144:147], v173
	ds_read_b128 v[148:151], v173 offset:4096
	ds_read_b128 v[152:155], v193 offset:32768
	ds_read_b128 v[156:159], v193 offset:36864
	ds_read_b128 v[160:163], v193 offset:40960
	ds_read_b128 v[164:167], v193 offset:45056
	s_waitcnt lgkmcnt(6)
	s_setprio 1
	v_mfma_f32_32x32x16_bf16 v[112:127], v[4:7], v[12:15], v[112:127]
	v_mfma_f32_32x32x16_bf16 v[80:95], v[8:11], v[12:15], v[80:95]
	v_mfma_f32_32x32x16_bf16 v[128:143], v[4:7], v[246:249], v[128:143]
	v_mfma_f32_32x32x16_bf16 v[96:111], v[8:11], v[246:249], v[96:111]
	v_mfma_f32_32x32x16_bf16 v[64:79], v[4:7], v[214:217], v[64:79]
	v_mfma_f32_32x32x16_bf16 v[16:31], v[8:11], v[214:217], v[16:31]
	v_mfma_f32_32x32x16_bf16 v[48:63], v[4:7], v[218:221], v[48:63]
	v_mfma_f32_32x32x16_bf16 v[32:47], v[8:11], v[218:221], v[32:47]
	s_setprio 0
	ds_read_b128 v[4:7], v174
	ds_read_b128 v[8:11], v174 offset:4096
	ds_read_b128 v[12:15], v194 offset:32768
	ds_read_b128 v[246:249], v194 offset:36864
	ds_read_b128 v[214:217], v194 offset:40960
	ds_read_b128 v[218:221], v194 offset:45056
	s_waitcnt lgkmcnt(6)
	s_setprio 1
	v_mfma_f32_32x32x16_bf16 v[112:127], v[144:147], v[152:155], v[112:127]
	v_mfma_f32_32x32x16_bf16 v[80:95], v[148:151], v[152:155], v[80:95]
	v_mfma_f32_32x32x16_bf16 v[128:143], v[144:147], v[156:159], v[128:143]
	v_mfma_f32_32x32x16_bf16 v[96:111], v[148:151], v[156:159], v[96:111]
	v_mfma_f32_32x32x16_bf16 v[64:79], v[144:147], v[160:163], v[64:79]
	v_mfma_f32_32x32x16_bf16 v[16:31], v[148:151], v[160:163], v[16:31]
	v_mfma_f32_32x32x16_bf16 v[48:63], v[144:147], v[164:167], v[48:63]
	v_mfma_f32_32x32x16_bf16 v[32:47], v[148:151], v[164:167], v[32:47]
	s_setprio 0
	ds_read_b128 v[144:147], v175
	ds_read_b128 v[148:151], v175 offset:4096
	ds_read_b128 v[152:155], v195 offset:32768
	ds_read_b128 v[156:159], v195 offset:36864
	ds_read_b128 v[160:163], v195 offset:40960
	ds_read_b128 v[164:167], v195 offset:45056
	s_waitcnt lgkmcnt(6)
	s_setprio 1
	v_mfma_f32_32x32x16_bf16 v[112:127], v[4:7], v[12:15], v[112:127]
	v_mfma_f32_32x32x16_bf16 v[80:95], v[8:11], v[12:15], v[80:95]
	v_mfma_f32_32x32x16_bf16 v[128:143], v[4:7], v[246:249], v[128:143]
	v_mfma_f32_32x32x16_bf16 v[96:111], v[8:11], v[246:249], v[96:111]
	v_mfma_f32_32x32x16_bf16 v[64:79], v[4:7], v[214:217], v[64:79]
	v_mfma_f32_32x32x16_bf16 v[16:31], v[8:11], v[214:217], v[16:31]
	v_mfma_f32_32x32x16_bf16 v[48:63], v[4:7], v[218:221], v[48:63]
	v_mfma_f32_32x32x16_bf16 v[32:47], v[8:11], v[218:221], v[32:47]
	s_setprio 0
	s_waitcnt lgkmcnt(0)
	s_setprio 1
	v_mfma_f32_32x32x16_bf16 v[112:127], v[144:147], v[152:155], v[112:127]
	v_mfma_f32_32x32x16_bf16 v[80:95], v[148:151], v[152:155], v[80:95]
	v_mfma_f32_32x32x16_bf16 v[128:143], v[144:147], v[156:159], v[128:143]
	v_mfma_f32_32x32x16_bf16 v[96:111], v[148:151], v[156:159], v[96:111]
	v_mfma_f32_32x32x16_bf16 v[64:79], v[144:147], v[160:163], v[64:79]
	v_mfma_f32_32x32x16_bf16 v[16:31], v[148:151], v[160:163], v[16:31]
	v_mfma_f32_32x32x16_bf16 v[48:63], v[144:147], v[164:167], v[48:63]
	v_mfma_f32_32x32x16_bf16 v[32:47], v[148:151], v[164:167], v[32:47]
	s_setprio 0
	s_cmp_eq_u32 s1, 1
	s_cbranch_scc1 .Lw13_last
	s_waitcnt vmcnt(0)
	s_barrier
	s_mov_b32 m0, s42
	s_nop 0
	global_load_lds_dwordx4 v168, s[22:23]
	s_add_u32 m0, m0, 0x2000
	s_nop 0
	global_load_lds_dwordx4 v169, s[22:23]
	s_add_u32 m0, m0, 0x2000
	s_nop 0
	global_load_lds_dwordx4 v170, s[22:23]
	s_add_u32 m0, m0, 0x2000
	s_nop 0
	global_load_lds_dwordx4 v171, s[22:23]
	s_add_u32 m0, m0, 0x2000
	s_nop 0
	global_load_lds_dwordx4 v168, s[24:25]
	s_add_u32 m0, m0, 0x2000
	s_nop 0
	global_load_lds_dwordx4 v169, s[24:25]
	s_add_u32 m0, m0, 0x2000
	s_nop 0
	global_load_lds_dwordx4 v170, s[24:25]
	s_add_u32 m0, m0, 0x2000
	s_nop 0
	global_load_lds_dwordx4 v171, s[24:25]
	s_add_u32 s22, s22, 0x80
	s_addc_u32 s23, s23, 0
	s_add_u32 s24, s24, 0x80
	s_addc_u32 s25, s25, 0
	ds_read_b128 v[4:7], v188
	ds_read_b128 v[8:11], v188 offset:4096
	ds_read_b128 v[12:15], v237 offset:32768
	ds_read_b128 v[246:249], v237 offset:36864
	ds_read_b128 v[214:217], v237 offset:40960
	ds_read_b128 v[218:221], v237 offset:45056
	ds_read_b128 v[144:147], v189
	ds_read_b128 v[148:151], v189 offset:4096
	ds_read_b128 v[152:155], v238 offset:32768
	ds_read_b128 v[156:159], v238 offset:36864
	ds_read_b128 v[160:163], v238 offset:40960
	ds_read_b128 v[164:167], v238 offset:45056
	s_waitcnt lgkmcnt(6)
	s_setprio 1
	v_mfma_f32_32x32x16_bf16 v[112:127], v[4:7], v[12:15], v[112:127]
	v_mfma_f32_32x32x16_bf16 v[80:95], v[8:11], v[12:15], v[80:95]
	v_mfma_f32_32x32x16_bf16 v[128:143], v[4:7], v[246:249], v[128:143]
	v_mfma_f32_32x32x16_bf16 v[96:111], v[8:11], v[246:249], v[96:111]
	v_mfma_f32_32x32x16_bf16 v[64:79], v[4:7], v[214:217], v[64:79]
	v_mfma_f32_32x32x16_bf16 v[16:31], v[8:11], v[214:217], v[16:31]
	v_mfma_f32_32x32x16_bf16 v[48:63], v[4:7], v[218:221], v[48:63]
	v_mfma_f32_32x32x16_bf16 v[32:47], v[8:11], v[218:221], v[32:47]
	s_setprio 0
	ds_read_b128 v[4:7], v190
	ds_read_b128 v[8:11], v190 offset:4096
	ds_read_b128 v[12:15], v239 offset:32768
	ds_read_b128 v[246:249], v239 offset:36864
	ds_read_b128 v[214:217], v239 offset:40960
	ds_read_b128 v[218:221], v239 offset:45056
	s_waitcnt lgkmcnt(6)
	s_setprio 1
	v_mfma_f32_32x32x16_bf16 v[112:127], v[144:147], v[152:155], v[112:127]
	v_mfma_f32_32x32x16_bf16 v[80:95], v[148:151], v[152:155], v[80:95]
	v_mfma_f32_32x32x16_bf16 v[128:143], v[144:147], v[156:159], v[128:143]
	v_mfma_f32_32x32x16_bf16 v[96:111], v[148:151], v[156:159], v[96:111]
	v_mfma_f32_32x32x16_bf16 v[64:79], v[144:147], v[160:163], v[64:79]
	v_mfma_f32_32x32x16_bf16 v[16:31], v[148:151], v[160:163], v[16:31]
	v_mfma_f32_32x32x16_bf16 v[48:63], v[144:147], v[164:167], v[48:63]
	v_mfma_f32_32x32x16_bf16 v[32:47], v[148:151], v[164:167], v[32:47]
	s_setprio 0
	ds_read_b128 v[144:147], v191
	ds_read_b128 v[148:151], v191 offset:4096
	ds_read_b128 v[152:155], v240 offset:32768
	ds_read_b128 v[156:159], v240 offset:36864
	ds_read_b128 v[160:163], v240 offset:40960
	ds_read_b128 v[164:167], v240 offset:45056
	s_waitcnt lgkmcnt(6)
	s_setprio 1
	v_mfma_f32_32x32x16_bf16 v[112:127], v[4:7], v[12:15], v[112:127]
	v_mfma_f32_32x32x16_bf16 v[80:95], v[8:11], v[12:15], v[80:95]
	v_mfma_f32_32x32x16_bf16 v[128:143], v[4:7], v[246:249], v[128:143]
	v_mfma_f32_32x32x16_bf16 v[96:111], v[8:11], v[246:249], v[96:111]
	v_mfma_f32_32x32x16_bf16 v[64:79], v[4:7], v[214:217], v[64:79]
	v_mfma_f32_32x32x16_bf16 v[16:31], v[8:11], v[214:217], v[16:31]
	v_mfma_f32_32x32x16_bf16 v[48:63], v[4:7], v[218:221], v[48:63]
	v_mfma_f32_32x32x16_bf16 v[32:47], v[8:11], v[218:221], v[32:47]
	s_setprio 0
	s_waitcnt lgkmcnt(0)
	s_setprio 1
	v_mfma_f32_32x32x16_bf16 v[112:127], v[144:147], v[152:155], v[112:127]
	v_mfma_f32_32x32x16_bf16 v[80:95], v[148:151], v[152:155], v[80:95]
	v_mfma_f32_32x32x16_bf16 v[128:143], v[144:147], v[156:159], v[128:143]
	v_mfma_f32_32x32x16_bf16 v[96:111], v[148:151], v[156:159], v[96:111]
	v_mfma_f32_32x32x16_bf16 v[64:79], v[144:147], v[160:163], v[64:79]
	v_mfma_f32_32x32x16_bf16 v[16:31], v[148:151], v[160:163], v[16:31]
	v_mfma_f32_32x32x16_bf16 v[48:63], v[144:147], v[164:167], v[48:63]
	v_mfma_f32_32x32x16_bf16 v[32:47], v[148:151], v[164:167], v[32:47]
	s_setprio 0
	s_add_i32 s1, s1, -1
	s_branch .Lw13_loop
